# QK segments of the four attention loops: hipcc's lgkmcnt(0) drains behind freshly issued K-fragment reads replaced by exact counted waits; on top of v25
# baseline (speedup 1.0000x reference)
; #define MFMA32(a, b, c) __builtin_amdgcn_mfma_f32_32x32x16_bf16((a), (b), (c), 0, 0, 0)
; template <bool MLA>
; DI void attn_unit(LAS unsigned char* lds, const bf16* Qp, int qstride, const bf16* Kp, int kstride, const bf16* KRp, const bf16* Vp, int vstride,
;                   bf16* Op, int ostride, int t_lo, int t_hi, int qc, bool active, int wave, int lane) {
;     ...
;         const bool doit = active && t <= qc && (MLA || t >= qc - 8);
;         if (doit) {
; #pragma unroll
;             for (int i = 0; i < 16; ++i) { s0[i] = 0.f; s1[i] = 0.f; }
;             {
;                 int kx = kxor, kr_ = krx; asm volatile("" : "+v"(kx), "+v"(kr_));
;     ...
;                 bf16x8 ka[3][2];
;                 ka[0][0] = AT_KLD(0, 0); ka[0][1] = AT_KLD(0, 1); ka[1][0] = AT_KLD(1, 0); ka[1][1] = AT_KLD(1, 1);
; #pragma unroll
;                 for (int ks = 0; ks < NKS; ++ks) {
;                     if (ks + 2 < NKS) { ka[(ks + 2) % 3][0] = AT_KLD(ks + 2, 0); ka[(ks + 2) % 3][1] = AT_KLD(ks + 2, 1); }
;                     __builtin_amdgcn_sched_barrier(0);
;                     s0 = MFMA32(ka[ks % 3][0], qf[ks], s0); s1 = MFMA32(ka[ks % 3][1], qf[ks], s1);
;                     __builtin_amdgcn_sched_barrier(0);
;                 }
.LBB0_584:
	s_mul_i32 s86, s84, 0xa000
	s_add_i32 s85, s86, 0
	s_cmp_le_i32 s80, s81
	s_cselect_b64 s[6:7], -1, 0
	s_cmp_ge_i32 s80, s82
	s_cselect_b64 s[50:51], -1, 0
	s_and_b64 s[50:51], s[6:7], s[50:51]
	v_cndmask_b32_e64 v64, 0, 1, s[50:51]
	v_cmp_ne_u32_e64 s[6:7], 1, v64
	s_andn2_b64 vcc, exec, s[50:51]
	s_cbranch_vccnz .LBB0_589
	v_mov_b32_e32 v64, v183
	v_mov_b32_e32 v65, v185
	v_add_u32_e32 v174, s85, v184
	v_lshlrev_b32_e32 v175, 4, v64
	v_add_u32_e32 v68, v174, v175
	v_xad_u32 v72, v175, 32, v174
	ds_read_b128 v[64:67], v68
	ds_read_b128 v[68:71], v68 offset:8192
	ds_read_b128 v[148:151], v72
	ds_read_b128 v[152:155], v72 offset:8192
	v_xad_u32 v72, v175, 64, v174
	ds_read_b128 v[156:159], v72
	ds_read_b128 v[162:165], v72 offset:8192
	s_waitcnt lgkmcnt(5)
	v_mfma_f32_32x32x16_bf16 v[80:95], v[64:67], v[96:99], 0
	s_waitcnt lgkmcnt(4)
	v_mfma_f32_32x32x16_bf16 v[64:79], v[68:71], v[96:99], 0
	v_xad_u32 v170, v175, s73, v174
	ds_read_b128 v[166:169], v170
	ds_read_b128 v[170:173], v170 offset:8192
	s_waitcnt lgkmcnt(5)
	v_mfma_f32_32x32x16_bf16 v[80:95], v[148:151], v[100:103], v[80:95]
	s_waitcnt lgkmcnt(4)
	v_mfma_f32_32x32x16_bf16 v[64:79], v[152:155], v[100:103], v[64:79]
	v_xad_u32 v152, v175, s64, v174
	ds_read_b128 v[148:151], v152
	ds_read_b128 v[152:155], v152 offset:8192
	s_waitcnt lgkmcnt(5)
	v_mfma_f32_32x32x16_bf16 v[80:95], v[156:159], v[104:107], v[80:95]
	s_waitcnt lgkmcnt(4)
	v_mfma_f32_32x32x16_bf16 v[64:79], v[162:165], v[104:107], v[64:79]
	v_xad_u32 v162, v175, s74, v174
	ds_read_b128 v[156:159], v162
	ds_read_b128 v[162:165], v162 offset:8192
	s_waitcnt lgkmcnt(5)
	v_mfma_f32_32x32x16_bf16 v[80:95], v[166:169], v[108:111], v[80:95]
	s_waitcnt lgkmcnt(4)
	v_mfma_f32_32x32x16_bf16 v[64:79], v[170:173], v[108:111], v[64:79]
	v_xad_u32 v170, v175, s75, v174
	ds_read_b128 v[166:169], v170
	ds_read_b128 v[170:173], v170 offset:8192
	s_waitcnt lgkmcnt(5)
	v_mfma_f32_32x32x16_bf16 v[80:95], v[148:151], v[112:115], v[80:95]
	s_waitcnt lgkmcnt(4)
	v_mfma_f32_32x32x16_bf16 v[64:79], v[152:155], v[112:115], v[64:79]
	v_xad_u32 v152, v175, s76, v174
	ds_read_b128 v[148:151], v152
	ds_read_b128 v[152:155], v152 offset:8192
	s_waitcnt lgkmcnt(5)
	v_mfma_f32_32x32x16_bf16 v[80:95], v[156:159], v[116:119], v[80:95]
	s_waitcnt lgkmcnt(4)
	v_mfma_f32_32x32x16_bf16 v[64:79], v[162:165], v[116:119], v[64:79]
	s_waitcnt lgkmcnt(3)
	v_mfma_f32_32x32x16_bf16 v[80:95], v[166:169], v[120:123], v[80:95]
	s_waitcnt lgkmcnt(2)
	v_mfma_f32_32x32x16_bf16 v[64:79], v[170:173], v[120:123], v[64:79]
	s_waitcnt lgkmcnt(1)
	v_mfma_f32_32x32x16_bf16 v[80:95], v[148:151], v[124:127], v[80:95]
	s_waitcnt lgkmcnt(0)
	v_mfma_f32_32x32x16_bf16 v[64:79], v[152:155], v[124:127], v[64:79]
	s_cmp_lt_i32 s83, 5
	s_mov_b64 s[50:51], -1
	s_cbranch_scc0 .LBB0_587
; template <bool MLA>
; DI void attn_unit(LAS unsigned char* lds, const bf16* Qp, int qstride, const bf16* Kp, int kstride, const bf16* KRp, const bf16* Vp, int vstride,
;                   bf16* Op, int ostride, int t_lo, int t_hi, int qc, bool active, int wave, int lane) {
;     ...
;                 } else {
;                     const int dbase = 64 * delta + (wave & 1) * 32 + r - 4 * h + 63;
; #pragma unroll
;                     for (int i = 0; i < 16; ++i) {
;                         const int kk = (i & 3) + 8 * (i >> 2);
;                         int i0 = dbase - kk; i0 = i0 > 319 ? 319 : i0;
;                         int i1 = dbase - kk - 32; i1 = i1 > 319 ? 319 : i1;
;                         s0[i] += tab[i0]; s1[i] += tab[i1];
;                     }
;                 }
	v_add_u32_e32 v150, 26, v191
	v_min_i32_e32 v151, 0x13f, v150
	v_min_i32_e32 v150, 0x15f, v150
	v_lshl_add_u32 v150, v150, 2, s61
	v_add_u32_e32 v152, 0xffffff80, v150
	v_add_u32_e32 v150, 25, v191
	v_min_i32_e32 v153, 0x13f, v150
	v_min_i32_e32 v150, 0x15f, v150
	v_lshl_add_u32 v150, v150, 2, s61
	v_add_u32_e32 v148, 27, v191
	v_add_u32_e32 v156, 0xffffff80, v150
	v_add_u32_e32 v150, 24, v191
	v_min_i32_e32 v149, 0x13f, v148
	v_min_i32_e32 v148, 0x15f, v148
	v_min_i32_e32 v154, 0x13f, v150
	v_min_i32_e32 v150, 0x15f, v150
	v_lshl_add_u32 v148, v148, 2, s61
	v_lshl_add_u32 v150, v150, 2, s61
	v_lshl_add_u32 v149, v149, 2, s61
	v_add_u32_e32 v148, 0xffffff80, v148
	v_lshl_add_u32 v151, v151, 2, s61
	v_lshl_add_u32 v153, v153, 2, s61
	v_add_u32_e32 v158, 0xffffff80, v150
	v_add_u32_e32 v162, 17, v191
	v_lshl_add_u32 v157, v154, 2, s61
	ds_read_b32 v150, v149
	ds_read_b32 v154, v148
	ds_read_b32 v151, v151
	ds_read_b32 v155, v152
	ds_read_b32 v148, v153
	ds_read_b32 v152, v156
	ds_read_b32 v149, v157
	ds_read_b32 v153, v158
	v_add_u32_e32 v156, 19, v191
	v_add_u32_e32 v158, 18, v191
	v_min_i32_e32 v163, 0x13f, v162
	v_min_i32_e32 v162, 0x15f, v162
	v_add_u32_e32 v164, 16, v191
	v_min_i32_e32 v157, 0x13f, v156
	v_min_i32_e32 v156, 0x15f, v156
	v_min_i32_e32 v159, 0x13f, v158
	v_min_i32_e32 v158, 0x15f, v158
	v_lshl_add_u32 v162, v162, 2, s61
	v_min_i32_e32 v165, 0x13f, v164
	v_min_i32_e32 v164, 0x15f, v164
	v_lshl_add_u32 v157, v157, 2, s61
	v_lshl_add_u32 v156, v156, 2, s61
	v_lshl_add_u32 v158, v158, 2, s61
	v_add_u32_e32 v162, 0xffffff80, v162
	v_lshl_add_u32 v164, v164, 2, s61
	v_add_u32_e32 v156, 0xffffff80, v156
	v_lshl_add_u32 v159, v159, 2, s61
	v_add_u32_e32 v158, 0xffffff80, v158
	v_lshl_add_u32 v163, v163, 2, s61
	v_lshl_add_u32 v166, v165, 2, s61
	v_add_u32_e32 v167, 0xffffff80, v164
	ds_read_b32 v164, v157
	ds_read_b32 v180, v156
	ds_read_b32 v165, v159
	ds_read_b32 v181, v158
	ds_read_b32 v168, v163
	ds_read_b32 v178, v162
	ds_read_b32 v169, v166
	ds_read_b32 v179, v167
	v_add_u32_e32 v162, 9, v191
	v_min_i32_e32 v163, 0x13f, v162
	v_min_i32_e32 v162, 0x15f, v162
	v_lshl_add_u32 v162, v162, 2, s61
	v_add_u32_e32 v158, 10, v191
	v_add_u32_e32 v170, 0xffffff80, v162
	v_add_u32_e32 v162, 8, v191
	v_add_u32_e32 v156, 11, v191
	v_min_i32_e32 v159, 0x13f, v158
	v_min_i32_e32 v158, 0x15f, v158
	v_min_i32_e32 v166, 0x13f, v162
	v_min_i32_e32 v162, 0x15f, v162
	v_min_i32_e32 v157, 0x13f, v156
	v_min_i32_e32 v156, 0x15f, v156
	v_lshl_add_u32 v158, v158, 2, s61
	v_lshl_add_u32 v162, v162, 2, s61
	v_lshl_add_u32 v157, v157, 2, s61
	v_lshl_add_u32 v156, v156, 2, s61
	v_add_u32_e32 v158, 0xffffff80, v158
	v_lshl_add_u32 v163, v163, 2, s61
	v_add_u32_e32 v173, 0xffffff80, v162
	v_add_u32_e32 v156, 0xffffff80, v156
	v_lshl_add_u32 v159, v159, 2, s61
	v_lshl_add_u32 v171, v166, 2, s61
	ds_read_b32 v166, v157
	ds_read_b32 v176, v156
	ds_read_b32 v167, v159
	ds_read_b32 v177, v158
	ds_read_b32 v162, v163
	ds_read_b32 v172, v170
	ds_read_b32 v163, v171
	ds_read_b32 v173, v173
	v_add_u32_e32 v158, 2, v191
	v_min_i32_e32 v159, 0x13f, v158
	v_min_i32_e32 v158, 0x15f, v158
	v_lshl_add_u32 v158, v158, 2, s61
	v_add_u32_e32 v170, 0xffffff80, v158
	v_add_u32_e32 v158, 1, v191
	v_add_u32_e32 v156, 3, v191
	v_min_i32_e32 v171, 0x13f, v158
	v_min_i32_e32 v158, 0x15f, v158
	v_min_i32_e32 v157, 0x13f, v156
	v_min_i32_e32 v156, 0x15f, v156
	v_lshl_add_u32 v158, v158, 2, s61
	v_lshl_add_u32 v156, v156, 2, s61
	v_add_u32_e32 v174, 0xffffff80, v158
	v_min_i32_e32 v158, 0x13f, v191
	v_min_i32_e32 v175, 0x15f, v191
	v_lshl_add_u32 v157, v157, 2, s61
	v_add_u32_e32 v156, 0xffffff80, v156
	v_lshl_add_u32 v159, v159, 2, s61
	v_lshl_add_u32 v193, v158, 2, s61
	v_lshl_add_u32 v158, v175, 2, s61
	v_lshl_add_u32 v171, v171, 2, s61
	v_add_u32_e32 v175, 0xffffff80, v158
	ds_read_b32 v158, v157
	ds_read_b32 v194, v156
	ds_read_b32 v156, v171
	ds_read_b32 v157, v193
	ds_read_b32 v159, v159
	ds_read_b32 v195, v170
	ds_read_b32 v196, v174
	ds_read_b32 v197, v175
	s_waitcnt lgkmcnt(0)
	v_pk_add_f32 v[156:157], v[94:95], v[156:157]
	s_waitcnt lgkmcnt(3)
	v_pk_add_f32 v[158:159], v[92:93], v[158:159]
	v_pk_add_f32 v[162:163], v[90:91], v[162:163]
	v_pk_add_f32 v[166:167], v[88:89], v[166:167]
	v_pk_add_f32 v[170:171], v[86:87], v[168:169]
	v_pk_add_f32 v[174:175], v[84:85], v[164:165]
	v_pk_add_f32 v[148:149], v[82:83], v[148:149]
	v_pk_add_f32 v[150:151], v[80:81], v[150:151]
	s_waitcnt lgkmcnt(0)
	v_pk_add_f32 v[164:165], v[78:79], v[196:197]
	v_pk_add_f32 v[168:169], v[76:77], v[194:195]
	v_pk_add_f32 v[172:173], v[74:75], v[172:173]
	v_pk_add_f32 v[176:177], v[72:73], v[176:177]
	v_pk_add_f32 v[178:179], v[70:71], v[178:179]
	v_pk_add_f32 v[180:181], v[68:69], v[180:181]
	v_pk_add_f32 v[152:153], v[66:67], v[152:153]
	v_pk_add_f32 v[154:155], v[64:65], v[154:155]
	s_mov_b64 s[50:51], 0

; #define MFMA32(a, b, c) __builtin_amdgcn_mfma_f32_32x32x16_bf16((a), (b), (c), 0, 0, 0)
; template <bool MLA>
; DI void attn_unit(LAS unsigned char* lds, const bf16* Qp, int qstride, const bf16* Kp, int kstride, const bf16* KRp, const bf16* Vp, int vstride,
;                   bf16* Op, int ostride, int t_lo, int t_hi, int qc, bool active, int wave, int lane) {
;     ...
;         const bool doit = active && t <= qc && (MLA || t >= qc - 8);
;         if (doit) {
; #pragma unroll
;             for (int i = 0; i < 16; ++i) { s0[i] = 0.f; s1[i] = 0.f; }
;             {
;                 int kx = kxor, kr_ = krx; asm volatile("" : "+v"(kx), "+v"(kr_));
;     ...
;                 bf16x8 ka[3][2];
;                 ka[0][0] = AT_KLD(0, 0); ka[0][1] = AT_KLD(0, 1); ka[1][0] = AT_KLD(1, 0); ka[1][1] = AT_KLD(1, 1);
; #pragma unroll
;                 for (int ks = 0; ks < NKS; ++ks) {
;                     if (ks + 2 < NKS) { ka[(ks + 2) % 3][0] = AT_KLD(ks + 2, 0); ka[(ks + 2) % 3][1] = AT_KLD(ks + 2, 1); }
;                     __builtin_amdgcn_sched_barrier(0);
;                     s0 = MFMA32(ka[ks % 3][0], qf[ks], s0); s1 = MFMA32(ka[ks % 3][1], qf[ks], s1);
;                     __builtin_amdgcn_sched_barrier(0);
;                 }
.LBB0_621:
	s_mul_i32 s53, s79, 0xa000
	s_and_b64 vcc, exec, s[4:5]
	s_add_i32 s52, s53, 0
	s_cbranch_vccnz .LBB0_626
	v_mov_b32_e32 v64, v183
	v_mov_b32_e32 v65, v185
	v_add_u32_e32 v158, s52, v184
	v_lshlrev_b32_e32 v159, 4, v64
	v_add_u32_e32 v68, v158, v159
	v_xad_u32 v72, v159, 32, v158
	ds_read_b128 v[64:67], v68
	ds_read_b128 v[68:71], v68 offset:8192
	ds_read_b128 v[146:149], v72
	ds_read_b128 v[150:153], v72 offset:8192
	v_xad_u32 v72, v159, 64, v158
	ds_read_b128 v[154:157], v72
	ds_read_b128 v[162:165], v72 offset:8192
	s_waitcnt lgkmcnt(5)
	v_mfma_f32_32x32x16_bf16 v[80:95], v[64:67], v[124:127], 0
	s_waitcnt lgkmcnt(4)
	v_mfma_f32_32x32x16_bf16 v[64:79], v[68:71], v[124:127], 0
	v_xad_u32 v170, v159, s73, v158
	ds_read_b128 v[166:169], v170
	ds_read_b128 v[170:173], v170 offset:8192
	s_waitcnt lgkmcnt(5)
	v_mfma_f32_32x32x16_bf16 v[80:95], v[146:149], v[120:123], v[80:95]
	s_waitcnt lgkmcnt(4)
	v_mfma_f32_32x32x16_bf16 v[64:79], v[150:153], v[120:123], v[64:79]
	v_xad_u32 v150, v159, s64, v158
	ds_read_b128 v[146:149], v150
	ds_read_b128 v[150:153], v150 offset:8192
	s_waitcnt lgkmcnt(5)
	v_mfma_f32_32x32x16_bf16 v[80:95], v[154:157], v[116:119], v[80:95]
	s_waitcnt lgkmcnt(4)
	v_mfma_f32_32x32x16_bf16 v[64:79], v[162:165], v[116:119], v[64:79]
	v_xad_u32 v162, v159, s74, v158
	ds_read_b128 v[154:157], v162
	ds_read_b128 v[162:165], v162 offset:8192
	s_waitcnt lgkmcnt(5)
	v_mfma_f32_32x32x16_bf16 v[80:95], v[166:169], v[112:115], v[80:95]
	s_waitcnt lgkmcnt(4)
	v_mfma_f32_32x32x16_bf16 v[64:79], v[170:173], v[112:115], v[64:79]
	v_xad_u32 v170, v159, s75, v158
	ds_read_b128 v[166:169], v170
	ds_read_b128 v[170:173], v170 offset:8192
	s_waitcnt lgkmcnt(5)
	v_mfma_f32_32x32x16_bf16 v[80:95], v[146:149], v[108:111], v[80:95]
	s_waitcnt lgkmcnt(4)
	v_mfma_f32_32x32x16_bf16 v[64:79], v[150:153], v[108:111], v[64:79]
	v_xad_u32 v150, v159, s76, v158
	ds_read_b128 v[146:149], v150
	ds_read_b128 v[150:153], v150 offset:8192
	s_waitcnt lgkmcnt(5)
	v_mfma_f32_32x32x16_bf16 v[80:95], v[154:157], v[104:107], v[80:95]
	s_waitcnt lgkmcnt(4)
	v_mfma_f32_32x32x16_bf16 v[64:79], v[162:165], v[104:107], v[64:79]
	s_waitcnt lgkmcnt(3)
	v_mfma_f32_32x32x16_bf16 v[80:95], v[166:169], v[100:103], v[80:95]
	s_waitcnt lgkmcnt(2)
	v_mfma_f32_32x32x16_bf16 v[64:79], v[170:173], v[100:103], v[64:79]
	s_waitcnt lgkmcnt(1)
	v_mfma_f32_32x32x16_bf16 v[80:95], v[146:149], v[96:99], v[80:95]
	s_waitcnt lgkmcnt(0)
	v_mfma_f32_32x32x16_bf16 v[64:79], v[150:153], v[96:99], v[64:79]
	s_cmp_gt_u32 s80, 3
	s_mov_b64 s[50:51], -1
	s_cbranch_scc0 .LBB0_624
; template <bool MLA>
; DI void attn_unit(LAS unsigned char* lds, const bf16* Qp, int qstride, const bf16* Kp, int kstride, const bf16* KRp, const bf16* Vp, int vstride,
;                   bf16* Op, int ostride, int t_lo, int t_hi, int qc, bool active, int wave, int lane) {
;     ...
;                 } else {
;                     const int dbase = 64 * delta + (wave & 1) * 32 + r - 4 * h + 63;
; #pragma unroll
;                     for (int i = 0; i < 16; ++i) {
;                         const int kk = (i & 3) + 8 * (i >> 2);
;                         int i0 = dbase - kk; i0 = i0 > 319 ? 319 : i0;
;                         int i1 = dbase - kk - 32; i1 = i1 > 319 ? 319 : i1;
;                         s0[i] += tab[i0]; s1[i] += tab[i1];
;                     }
;                 }
	v_add_u32_e32 v154, s0, v187
	v_add_u32_e32 v148, 0x23e, v154
	v_min_i32_e32 v149, 0x13f, v148
	v_min_i32_e32 v148, 0x15f, v148
	v_lshl_add_u32 v148, v148, 2, s61
	v_add_u32_e32 v150, 0xffffff80, v148
	v_add_u32_e32 v148, 0x23d, v154
	v_min_i32_e32 v151, 0x13f, v148
	v_min_i32_e32 v148, 0x15f, v148
	v_lshl_add_u32 v148, v148, 2, s61
	v_add_u32_e32 v146, 0x23f, v154
	v_add_u32_e32 v155, 0xffffff80, v148
	v_add_u32_e32 v148, 0x23c, v154
	v_min_i32_e32 v147, 0x13f, v146
	v_min_i32_e32 v146, 0x15f, v146
	v_min_i32_e32 v152, 0x13f, v148
	v_min_i32_e32 v148, 0x15f, v148
	v_lshl_add_u32 v146, v146, 2, s61
	v_lshl_add_u32 v148, v148, 2, s61
	v_add_u32_e32 v159, 0x235, v154
	v_lshl_add_u32 v147, v147, 2, s61
	v_add_u32_e32 v146, 0xffffff80, v146
	v_lshl_add_u32 v149, v149, 2, s61
	v_lshl_add_u32 v151, v151, 2, s61
	v_add_u32_e32 v157, 0xffffff80, v148
	v_min_i32_e32 v162, 0x13f, v159
	v_lshl_add_u32 v156, v152, 2, s61
	ds_read_b32 v148, v147
	ds_read_b32 v152, v146
	ds_read_b32 v149, v149
	ds_read_b32 v153, v150
	ds_read_b32 v146, v151
	ds_read_b32 v150, v155
	ds_read_b32 v147, v156
	ds_read_b32 v151, v157
	v_add_u32_e32 v155, 0x237, v154
	v_add_u32_e32 v157, 0x236, v154
	v_min_i32_e32 v159, 0x15f, v159
	v_lshl_add_u32 v164, v162, 2, s61
	v_add_u32_e32 v162, 0x234, v154
	v_min_i32_e32 v156, 0x13f, v155
	v_min_i32_e32 v155, 0x15f, v155
	v_min_i32_e32 v158, 0x13f, v157
	v_min_i32_e32 v157, 0x15f, v157
	v_lshl_add_u32 v159, v159, 2, s61
	v_min_i32_e32 v163, 0x13f, v162
	v_min_i32_e32 v162, 0x15f, v162
	v_lshl_add_u32 v156, v156, 2, s61
	v_lshl_add_u32 v155, v155, 2, s61
	v_lshl_add_u32 v157, v157, 2, s61
	v_add_u32_e32 v159, 0xffffff80, v159
	v_lshl_add_u32 v162, v162, 2, s61
	v_add_u32_e32 v155, 0xffffff80, v155
	v_lshl_add_u32 v158, v158, 2, s61
	v_add_u32_e32 v157, 0xffffff80, v157
	v_lshl_add_u32 v165, v163, 2, s61
	v_add_u32_e32 v168, 0xffffff80, v162
	ds_read_b32 v162, v156
	ds_read_b32 v178, v155
	ds_read_b32 v163, v158
	ds_read_b32 v179, v157
	ds_read_b32 v166, v164
	ds_read_b32 v176, v159
	ds_read_b32 v167, v165
	ds_read_b32 v177, v168
	v_add_u32_e32 v159, 0x22d, v154
	v_min_i32_e32 v164, 0x13f, v159
	v_add_u32_e32 v157, 0x22e, v154
	v_lshl_add_u32 v168, v164, 2, s61
	v_add_u32_e32 v164, 0x22c, v154
	v_add_u32_e32 v155, 0x22f, v154
	v_min_i32_e32 v158, 0x13f, v157
	v_min_i32_e32 v157, 0x15f, v157
	v_min_i32_e32 v159, 0x15f, v159
	v_min_i32_e32 v165, 0x13f, v164
	v_min_i32_e32 v164, 0x15f, v164
	v_min_i32_e32 v156, 0x13f, v155
	v_min_i32_e32 v155, 0x15f, v155
	v_lshl_add_u32 v157, v157, 2, s61
	v_lshl_add_u32 v159, v159, 2, s61
	v_lshl_add_u32 v164, v164, 2, s61
	v_lshl_add_u32 v156, v156, 2, s61
	v_lshl_add_u32 v155, v155, 2, s61
	v_lshl_add_u32 v158, v158, 2, s61
	v_add_u32_e32 v157, 0xffffff80, v157
	v_add_u32_e32 v159, 0xffffff80, v159
	v_add_u32_e32 v171, 0xffffff80, v164
	v_add_u32_e32 v155, 0xffffff80, v155
	v_lshl_add_u32 v169, v165, 2, s61
	ds_read_b32 v164, v156
	ds_read_b32 v174, v155
	ds_read_b32 v165, v158
	ds_read_b32 v175, v157
	ds_read_b32 v158, v168
	ds_read_b32 v170, v159
	ds_read_b32 v159, v169
	ds_read_b32 v171, v171
	v_add_u32_e32 v157, 0x226, v154
	v_min_i32_e32 v168, 0x13f, v157
	v_min_i32_e32 v157, 0x15f, v157
	v_lshl_add_u32 v157, v157, 2, s61
	v_add_u32_e32 v169, 0xffffff80, v157
	v_add_u32_e32 v157, 0x225, v154
	v_min_i32_e32 v172, 0x13f, v157
	v_min_i32_e32 v157, 0x15f, v157
	v_add_u32_e32 v155, 0x227, v154
	v_lshl_add_u32 v157, v157, 2, s61
	v_add_u32_e32 v154, 0x224, v154
	v_min_i32_e32 v156, 0x13f, v155
	v_min_i32_e32 v155, 0x15f, v155
	v_add_u32_e32 v173, 0xffffff80, v157
	v_min_i32_e32 v157, 0x13f, v154
	v_min_i32_e32 v154, 0x15f, v154
	v_lshl_add_u32 v155, v155, 2, s61
	v_lshl_add_u32 v154, v154, 2, s61
	v_lshl_add_u32 v156, v156, 2, s61
	v_add_u32_e32 v155, 0xffffff80, v155
	v_lshl_add_u32 v157, v157, 2, s61
	v_add_u32_e32 v193, 0xffffff80, v154
	v_lshl_add_u32 v168, v168, 2, s61
	v_lshl_add_u32 v172, v172, 2, s61
	ds_read_b32 v156, v156
	ds_read_b32 v190, v155
	ds_read_b32 v154, v172
	ds_read_b32 v155, v157
	ds_read_b32 v157, v168
	ds_read_b32 v191, v169
	ds_read_b32 v192, v173
	ds_read_b32 v193, v193
	s_waitcnt lgkmcnt(0)
	v_pk_add_f32 v[154:155], v[94:95], v[154:155]
	s_waitcnt lgkmcnt(3)
	v_pk_add_f32 v[156:157], v[92:93], v[156:157]
	v_pk_add_f32 v[158:159], v[90:91], v[158:159]
	v_pk_add_f32 v[164:165], v[88:89], v[164:165]
	v_pk_add_f32 v[168:169], v[86:87], v[166:167]
	v_pk_add_f32 v[172:173], v[84:85], v[162:163]
	v_pk_add_f32 v[146:147], v[82:83], v[146:147]
	v_pk_add_f32 v[148:149], v[80:81], v[148:149]
	s_waitcnt lgkmcnt(0)
	v_pk_add_f32 v[162:163], v[78:79], v[192:193]
	v_pk_add_f32 v[166:167], v[76:77], v[190:191]
	v_pk_add_f32 v[170:171], v[74:75], v[170:171]
	v_pk_add_f32 v[174:175], v[72:73], v[174:175]
	v_pk_add_f32 v[176:177], v[70:71], v[176:177]
	v_pk_add_f32 v[178:179], v[68:69], v[178:179]
	v_pk_add_f32 v[150:151], v[66:67], v[150:151]
	v_pk_add_f32 v[152:153], v[64:65], v[152:153]
	s_mov_b64 s[50:51], 0

; #define MFMA32(a, b, c) __builtin_amdgcn_mfma_f32_32x32x16_bf16((a), (b), (c), 0, 0, 0)
; template <bool MLA>
; DI void attn_unit(LAS unsigned char* lds, const bf16* Qp, int qstride, const bf16* Kp, int kstride, const bf16* KRp, const bf16* Vp, int vstride,
;                   bf16* Op, int ostride, int t_lo, int t_hi, int qc, bool active, int wave, int lane) {
;     ...
;         const bool doit = active && t <= qc && (MLA || t >= qc - 8);
;         if (doit) {
; #pragma unroll
;             for (int i = 0; i < 16; ++i) { s0[i] = 0.f; s1[i] = 0.f; }
;             {
;                 int kx = kxor, kr_ = krx; asm volatile("" : "+v"(kx), "+v"(kr_));
;     ...
;                 bf16x8 ka[3][2];
;                 ka[0][0] = AT_KLD(0, 0); ka[0][1] = AT_KLD(0, 1); ka[1][0] = AT_KLD(1, 0); ka[1][1] = AT_KLD(1, 1);
; #pragma unroll
;                 for (int ks = 0; ks < NKS; ++ks) {
;                     if (ks + 2 < NKS) { ka[(ks + 2) % 3][0] = AT_KLD(ks + 2, 0); ka[(ks + 2) % 3][1] = AT_KLD(ks + 2, 1); }
;                     __builtin_amdgcn_sched_barrier(0);
;                     s0 = MFMA32(ka[ks % 3][0], qf[ks], s0); s1 = MFMA32(ka[ks % 3][1], qf[ks], s1);
;                     __builtin_amdgcn_sched_barrier(0);
;                 }
.LBB0_845:
	s_mul_i32 s96, s93, 0xa000
	s_add_i32 s95, s96, 0
	s_cmp_le_u32 s94, s91
	s_cselect_b64 s[58:59], -1, 0
	s_cmp_gt_u32 s94, s91
	s_cbranch_scc1 .LBB0_847
	v_mov_b32_e32 v0, v233
	v_mov_b32_e32 v14, v235
	v_add_u32_e32 v15, s95, v234
	v_lshlrev_b32_e32 v0, 4, v0
	v_add_u32_e32 v6, v15, v0
	v_xad_u32 v80, v0, 32, v15
	ds_read_b128 v[2:5], v6
	ds_read_b128 v[6:9], v6 offset:8192
	ds_read_b128 v[10:13], v80
	ds_read_b128 v[224:227], v80 offset:8192
	v_xad_u32 v80, v0, 64, v15
	ds_read_b128 v[246:249], v80
	ds_read_b128 v[250:253], v80 offset:8192
	v_add_u32_e32 v243, s95, v236
	s_waitcnt lgkmcnt(5)
	v_mfma_f32_32x32x16_bf16 v[80:95], v[2:5], v[112:115], 0
	s_waitcnt lgkmcnt(4)
	v_mfma_f32_32x32x16_bf16 v[96:111], v[6:9], v[112:115], 0
	v_xad_u32 v6, v0, s71, v15
	ds_read_b128 v[2:5], v6
	ds_read_b128 v[6:9], v6 offset:8192
	s_waitcnt lgkmcnt(5)
	v_mfma_f32_32x32x16_bf16 v[80:95], v[10:13], v[116:119], v[80:95]
	s_waitcnt lgkmcnt(4)
	v_mfma_f32_32x32x16_bf16 v[96:111], v[224:227], v[116:119], v[96:111]
	v_xad_u32 v224, v0, s68, v15
	ds_read_b128 v[10:13], v224
	ds_read_b128 v[224:227], v224 offset:8192
	s_waitcnt lgkmcnt(5)
	v_mfma_f32_32x32x16_bf16 v[80:95], v[246:249], v[120:123], v[80:95]
	s_waitcnt lgkmcnt(4)
	v_mfma_f32_32x32x16_bf16 v[96:111], v[250:253], v[120:123], v[96:111]
	v_xad_u32 v245, v0, s72, v15
	ds_read_b128 v[246:249], v245
	ds_read_b128 v[250:253], v245 offset:8192
	s_waitcnt lgkmcnt(5)
	v_mfma_f32_32x32x16_bf16 v[80:95], v[2:5], v[124:127], v[80:95]
	s_waitcnt lgkmcnt(4)
	v_mfma_f32_32x32x16_bf16 v[96:111], v[6:9], v[124:127], v[96:111]
	v_xad_u32 v6, v0, s67, v15
	ds_read_b128 v[2:5], v6
	ds_read_b128 v[6:9], v6 offset:8192
	s_waitcnt lgkmcnt(5)
	v_mfma_f32_32x32x16_bf16 v[80:95], v[10:13], v[128:131], v[80:95]
	s_waitcnt lgkmcnt(4)
	v_mfma_f32_32x32x16_bf16 v[96:111], v[224:227], v[128:131], v[96:111]
	v_xad_u32 v0, v0, s73, v15
	ds_read_b128 v[10:13], v0
	ds_read_b128 v[224:227], v0 offset:8192
	s_waitcnt lgkmcnt(5)
	v_mfma_f32_32x32x16_bf16 v[80:95], v[246:249], v[132:135], v[80:95]
	s_waitcnt lgkmcnt(4)
	v_mfma_f32_32x32x16_bf16 v[96:111], v[250:253], v[132:135], v[96:111]
	v_lshlrev_b32_e32 v0, 4, v14
	v_add_u32_e32 v14, v243, v0
	ds_read_b128 v[246:249], v14 offset:32768
	ds_read_b128 v[250:253], v14 offset:36864
	s_waitcnt lgkmcnt(5)
	v_mfma_f32_32x32x16_bf16 v[80:95], v[2:5], v[136:139], v[80:95]
	s_waitcnt lgkmcnt(4)
	v_mfma_f32_32x32x16_bf16 v[96:111], v[6:9], v[136:139], v[96:111]
	v_xad_u32 v6, v0, 32, v243
	ds_read_b128 v[2:5], v6 offset:32768
	ds_read_b128 v[6:9], v6 offset:36864
	s_waitcnt lgkmcnt(5)
	v_mfma_f32_32x32x16_bf16 v[80:95], v[10:13], v[140:143], v[80:95]
	s_waitcnt lgkmcnt(4)
	v_mfma_f32_32x32x16_bf16 v[96:111], v[224:227], v[140:143], v[96:111]
	v_xad_u32 v14, v0, 64, v243
	ds_read_b128 v[10:13], v14 offset:32768
	ds_read_b128 v[224:227], v14 offset:36864
	s_waitcnt lgkmcnt(5)
	v_mfma_f32_32x32x16_bf16 v[80:95], v[246:249], v[144:147], v[80:95]
	s_waitcnt lgkmcnt(4)
	v_mfma_f32_32x32x16_bf16 v[96:111], v[250:253], v[144:147], v[96:111]
	v_xad_u32 v0, v0, s71, v243
	ds_read_b128 v[246:249], v0 offset:32768
	ds_read_b128 v[250:253], v0 offset:36864
	s_waitcnt lgkmcnt(5)
	v_mfma_f32_32x32x16_bf16 v[80:95], v[2:5], v[148:151], v[80:95]
	s_waitcnt lgkmcnt(4)
	v_mfma_f32_32x32x16_bf16 v[96:111], v[6:9], v[148:151], v[96:111]
	s_waitcnt lgkmcnt(3)
	v_mfma_f32_32x32x16_bf16 v[80:95], v[10:13], v[152:155], v[80:95]
	s_waitcnt lgkmcnt(2)
	v_mfma_f32_32x32x16_bf16 v[96:111], v[224:227], v[152:155], v[96:111]
	s_waitcnt lgkmcnt(1)
	v_mfma_f32_32x32x16_bf16 v[80:95], v[246:249], v[156:159], v[80:95]
	s_waitcnt lgkmcnt(0)
	v_mfma_f32_32x32x16_bf16 v[96:111], v[250:253], v[156:159], v[96:111]

; #define MFMA32(a, b, c) __builtin_amdgcn_mfma_f32_32x32x16_bf16((a), (b), (c), 0, 0, 0)
; template <bool MLA>
; DI void attn_unit(LAS unsigned char* lds, const bf16* Qp, int qstride, const bf16* Kp, int kstride, const bf16* KRp, const bf16* Vp, int vstride,
;                   bf16* Op, int ostride, int t_lo, int t_hi, int qc, bool active, int wave, int lane) {
;     ...
;         if (doit) {
; #pragma unroll
;             for (int i = 0; i < 16; ++i) { s0[i] = 0.f; s1[i] = 0.f; }
;             {
;                 int kx = kxor, kr_ = krx; asm volatile("" : "+v"(kx), "+v"(kr_));
;     ...
;                 bf16x8 ka[3][2];
;                 ka[0][0] = AT_KLD(0, 0); ka[0][1] = AT_KLD(0, 1); ka[1][0] = AT_KLD(1, 0); ka[1][1] = AT_KLD(1, 1);
; #pragma unroll
;                 for (int ks = 0; ks < NKS; ++ks) {
;                     if (ks + 2 < NKS) { ka[(ks + 2) % 3][0] = AT_KLD(ks + 2, 0); ka[(ks + 2) % 3][1] = AT_KLD(ks + 2, 1); }
;                     __builtin_amdgcn_sched_barrier(0);
;                     s0 = MFMA32(ka[ks % 3][0], qf[ks], s0); s1 = MFMA32(ka[ks % 3][1], qf[ks], s1);
;                     __builtin_amdgcn_sched_barrier(0);
;                 }
.LBB0_881:
	v_mov_b32_e32 v0, v233
	v_mov_b32_e32 v14, v235
	v_add_u32_e32 v15, s54, v234
	v_lshlrev_b32_e32 v0, 4, v0
	v_add_u32_e32 v6, v15, v0
	v_xad_u32 v80, v0, 32, v15
	ds_read_b128 v[2:5], v6
	ds_read_b128 v[6:9], v6 offset:8192
	ds_read_b128 v[10:13], v80
	ds_read_b128 v[208:211], v80 offset:8192
	v_xad_u32 v80, v0, 64, v15
	ds_read_b128 v[218:221], v80
	ds_read_b128 v[222:225], v80 offset:8192
	v_add_u32_e32 v214, s54, v236
	s_waitcnt lgkmcnt(5)
	v_mfma_f32_32x32x16_bf16 v[80:95], v[2:5], v[156:159], 0
	s_waitcnt lgkmcnt(4)
	v_mfma_f32_32x32x16_bf16 v[96:111], v[6:9], v[156:159], 0
	v_xad_u32 v6, v0, s71, v15
	ds_read_b128 v[2:5], v6
	ds_read_b128 v[6:9], v6 offset:8192
	s_waitcnt lgkmcnt(5)
	v_mfma_f32_32x32x16_bf16 v[80:95], v[10:13], v[152:155], v[80:95]
	s_waitcnt lgkmcnt(4)
	v_mfma_f32_32x32x16_bf16 v[96:111], v[208:211], v[152:155], v[96:111]
	v_xad_u32 v208, v0, s68, v15
	ds_read_b128 v[10:13], v208
	ds_read_b128 v[208:211], v208 offset:8192
	s_waitcnt lgkmcnt(5)
	v_mfma_f32_32x32x16_bf16 v[80:95], v[218:221], v[148:151], v[80:95]
	s_waitcnt lgkmcnt(4)
	v_mfma_f32_32x32x16_bf16 v[96:111], v[222:225], v[148:151], v[96:111]
	v_xad_u32 v215, v0, s72, v15
	ds_read_b128 v[218:221], v215
	ds_read_b128 v[222:225], v215 offset:8192
	s_waitcnt lgkmcnt(5)
	v_mfma_f32_32x32x16_bf16 v[80:95], v[2:5], v[144:147], v[80:95]
	s_waitcnt lgkmcnt(4)
	v_mfma_f32_32x32x16_bf16 v[96:111], v[6:9], v[144:147], v[96:111]
	v_xad_u32 v6, v0, s67, v15
	ds_read_b128 v[2:5], v6
	ds_read_b128 v[6:9], v6 offset:8192
	s_waitcnt lgkmcnt(5)
	v_mfma_f32_32x32x16_bf16 v[80:95], v[10:13], v[140:143], v[80:95]
	s_waitcnt lgkmcnt(4)
	v_mfma_f32_32x32x16_bf16 v[96:111], v[208:211], v[140:143], v[96:111]
	v_xad_u32 v0, v0, s73, v15
	ds_read_b128 v[10:13], v0
	ds_read_b128 v[208:211], v0 offset:8192
	s_waitcnt lgkmcnt(5)
	v_mfma_f32_32x32x16_bf16 v[80:95], v[218:221], v[136:139], v[80:95]
	s_waitcnt lgkmcnt(4)
	v_mfma_f32_32x32x16_bf16 v[96:111], v[222:225], v[136:139], v[96:111]
	v_lshlrev_b32_e32 v0, 4, v14
	v_add_u32_e32 v14, v214, v0
	ds_read_b128 v[218:221], v14 offset:32768
	ds_read_b128 v[222:225], v14 offset:36864
	s_waitcnt lgkmcnt(5)
	v_mfma_f32_32x32x16_bf16 v[80:95], v[2:5], v[132:135], v[80:95]
	s_waitcnt lgkmcnt(4)
	v_mfma_f32_32x32x16_bf16 v[96:111], v[6:9], v[132:135], v[96:111]
	v_xad_u32 v6, v0, 32, v214
	ds_read_b128 v[2:5], v6 offset:32768
	ds_read_b128 v[6:9], v6 offset:36864
	s_waitcnt lgkmcnt(5)
	v_mfma_f32_32x32x16_bf16 v[80:95], v[10:13], v[128:131], v[80:95]
	s_waitcnt lgkmcnt(4)
	v_mfma_f32_32x32x16_bf16 v[96:111], v[208:211], v[128:131], v[96:111]
	v_xad_u32 v14, v0, 64, v214
	ds_read_b128 v[10:13], v14 offset:32768
	ds_read_b128 v[208:211], v14 offset:36864
	s_waitcnt lgkmcnt(5)
	v_mfma_f32_32x32x16_bf16 v[80:95], v[218:221], v[124:127], v[80:95]
	s_waitcnt lgkmcnt(4)
	v_mfma_f32_32x32x16_bf16 v[96:111], v[222:225], v[124:127], v[96:111]
	v_xad_u32 v0, v0, s71, v214
	ds_read_b128 v[218:221], v0 offset:32768
	ds_read_b128 v[222:225], v0 offset:36864
	s_waitcnt lgkmcnt(5)
	v_mfma_f32_32x32x16_bf16 v[80:95], v[2:5], v[120:123], v[80:95]
	s_waitcnt lgkmcnt(4)
	v_mfma_f32_32x32x16_bf16 v[96:111], v[6:9], v[120:123], v[96:111]
	s_waitcnt lgkmcnt(3)
	v_mfma_f32_32x32x16_bf16 v[80:95], v[10:13], v[116:119], v[80:95]
	s_waitcnt lgkmcnt(2)
	v_mfma_f32_32x32x16_bf16 v[96:111], v[208:211], v[116:119], v[96:111]
	s_waitcnt lgkmcnt(1)
	v_mfma_f32_32x32x16_bf16 v[80:95], v[218:221], v[112:115], v[80:95]
	s_waitcnt lgkmcnt(0)
	v_mfma_f32_32x32x16_bf16 v[96:111], v[222:225], v[112:115], v[96:111]
	s_and_b64 vcc, exec, s[4:5]
	s_mov_b64 s[52:53], -1
	s_cbranch_vccnz .LBB0_876
